# P8 operands (ACT from P7 epilogue, w_down bf16 copy from P0) stored panel-blocked K-tile-major so each half-tile LDS-DMA load is a dense 16KB block
# speedup vs baseline: 1.0048x; 1.0048x over previous
.LBB0_22:
	s_cmpk_gt_u32 s18, 0x7bff
	s_cbranch_scc0 .LBB0_28
	s_cmp_gt_u32 s18, 0x127ff
	s_cbranch_scc0 .LBB0_25
	s_add_i32 s12, s18, 0xfffed800
	s_lshr_b32 s12, s12, 1
	s_and_b32 s13, s12, 0x7fffffc0
	s_and_b32 s12, s1, 0xfe0
	v_or_b32_e32 v2, s12, v47
	v_or_b32_e32 v32, s13, v48
	v_lshlrev_b32_e32 v2, 2, v2
	v_lshl_add_u64 v[34:35], s[46:47], 0, v[2:3]
	v_or_b32_e32 v2, 8, v32
	v_lshlrev_b64 v[6:7], 14, v[2:3]
	v_or_b32_e32 v2, 16, v32
	v_lshlrev_b64 v[12:13], 14, v[2:3]
	v_or_b32_e32 v2, 24, v32
	v_lshlrev_b64 v[14:15], 14, v[2:3]
	v_or_b32_e32 v2, 32, v32
	v_mov_b32_e32 v33, v3
	v_lshlrev_b64 v[20:21], 14, v[2:3]
	v_or_b32_e32 v2, 40, v32
	v_lshlrev_b64 v[4:5], 14, v[32:33]
	v_lshlrev_b64 v[22:23], 14, v[2:3]
	v_lshl_add_u64 v[4:5], v[34:35], 0, v[4:5]
	v_lshl_add_u64 v[8:9], v[34:35], 0, v[6:7]
	v_lshl_add_u64 v[12:13], v[34:35], 0, v[12:13]
	v_lshl_add_u64 v[16:17], v[34:35], 0, v[14:15]
	v_lshl_add_u64 v[20:21], v[34:35], 0, v[20:21]
	v_lshl_add_u64 v[24:25], v[34:35], 0, v[22:23]
	global_load_dwordx4 v[4:7], v[4:5], off
	s_nop 0
	global_load_dwordx4 v[8:11], v[8:9], off
	s_nop 0
	global_load_dwordx4 v[12:15], v[12:13], off
	s_nop 0
	global_load_dwordx4 v[16:19], v[16:17], off
	s_nop 0
	global_load_dwordx4 v[20:23], v[20:21], off
	s_nop 0
	global_load_dwordx4 v[24:27], v[24:25], off
	v_or_b32_e32 v2, 48, v32
	v_lshlrev_b64 v[28:29], 14, v[2:3]
	v_lshl_add_u64 v[28:29], v[34:35], 0, v[28:29]
	v_or_b32_e32 v2, 56, v32
	global_load_dwordx4 v[28:31], v[28:29], off
	v_lshlrev_b64 v[32:33], 14, v[2:3]
	v_lshl_add_u64 v[32:33], v[34:35], 0, v[32:33]
	global_load_dwordx4 v[32:35], v[32:33], off
	v_or_b32_e32 v2, s12, v48
	s_lshl_b32 s76, s13, 9
	v_lshl_add_u64 v[44:45], v[36:37], 0, s[76:77]
	v_and_b32_e32 v70, 0xff, v2
	v_and_b32_e32 v2, 0xffffff00, v2
	v_mul_u32_u24_e32 v2, 0x5600, v2
	v_lshl_add_u32 v2, v70, 7, v2
	v_lshl_add_u64 v[68:69], v[44:45], 0, v[2:3]
	s_waitcnt vmcnt(7)
	ds_write2_b32 v53, v4, v5 offset1:1
	ds_write2_b32 v53, v6, v7 offset0:2 offset1:3
	s_waitcnt vmcnt(6)
	ds_write2_b32 v54, v8, v9 offset1:1
	ds_write2_b32 v55, v10, v11 offset1:1
	s_waitcnt vmcnt(5)
	ds_write2_b32 v56, v12, v13 offset1:1
	ds_write2_b32 v57, v14, v15 offset1:1
	s_waitcnt vmcnt(4)
	ds_write2_b32 v58, v16, v17 offset1:1
	ds_write2_b32 v59, v18, v19 offset1:1
	s_waitcnt vmcnt(3)
	ds_write2_b32 v60, v20, v21 offset1:1
	ds_write2_b32 v61, v22, v23 offset1:1
	s_waitcnt vmcnt(2)
	ds_write2_b32 v62, v24, v25 offset1:1
	ds_write2_b32 v63, v26, v27 offset1:1
	s_waitcnt vmcnt(1)
	ds_write2_b32 v64, v28, v29 offset1:1
	ds_write2_b32 v65, v30, v31 offset1:1
	s_waitcnt vmcnt(0)
	ds_write2_b32 v66, v32, v33 offset1:1
	ds_write2_b32 v67, v34, v35 offset1:1
	s_waitcnt lgkmcnt(0)
	ds_read2_b32 v[4:5], v52 offset0:33 offset1:41
	ds_read2_b32 v[6:7], v52 offset1:8
	ds_read2_b32 v[8:9], v52 offset0:66 offset1:74
	ds_read2_b32 v[10:11], v52 offset0:99 offset1:107
	ds_read2_b32 v[12:13], v52 offset0:132 offset1:140
	ds_read2_b32 v[14:15], v52 offset0:165 offset1:173
	ds_read2_b32 v[16:17], v52 offset0:198 offset1:206
	ds_read2_b32 v[18:19], v52 offset0:231 offset1:239
	s_waitcnt lgkmcnt(6)
	v_bfe_u32 v2, v6, 16, 1
	v_bfe_u32 v20, v4, 16, 1
	s_waitcnt lgkmcnt(5)
	v_bfe_u32 v21, v8, 16, 1
	s_waitcnt lgkmcnt(4)
	v_bfe_u32 v22, v10, 16, 1
	s_waitcnt lgkmcnt(3)
	v_bfe_u32 v23, v12, 16, 1
	s_waitcnt lgkmcnt(2)
	v_bfe_u32 v24, v14, 16, 1
	s_waitcnt lgkmcnt(1)
	v_bfe_u32 v25, v16, 16, 1
	s_waitcnt lgkmcnt(0)
	v_bfe_u32 v26, v18, 16, 1
	v_bfe_u32 v28, v5, 16, 1
	v_bfe_u32 v29, v9, 16, 1
	v_add3_u32 v2, v6, v2, s20
	v_bfe_u32 v27, v7, 16, 1
	v_bfe_u32 v30, v11, 16, 1
	v_add3_u32 v4, v4, v20, s20
	v_add3_u32 v6, v8, v21, s20
	v_add3_u32 v8, v10, v22, s20
	v_add3_u32 v10, v12, v23, s20
	v_add3_u32 v12, v14, v24, s20
	v_add3_u32 v14, v16, v25, s20
	v_add3_u32 v16, v18, v26, s20
	v_add3_u32 v18, v5, v28, s20
	v_add3_u32 v5, v9, v29, s20
	v_lshrrev_b32_e32 v2, 16, v2
	v_add3_u32 v7, v7, v27, s20
	v_lshrrev_b32_e32 v6, 16, v6
	v_lshrrev_b32_e32 v9, 16, v10
	v_lshrrev_b32_e32 v10, 16, v14
	v_lshrrev_b32_e32 v20, 16, v5
	v_and_or_b32 v4, v4, s21, v2
	v_add3_u32 v2, v11, v30, s20
	v_lshrrev_b32_e32 v14, 16, v7
	v_and_or_b32 v5, v8, s21, v6
	v_and_or_b32 v6, v12, s21, v9
	v_and_or_b32 v7, v16, s21, v10
	v_and_or_b32 v9, v2, s21, v20
	v_bfe_u32 v2, v13, 16, 1
	global_store_dwordx4 v[68:69], v[4:7], off
	v_add3_u32 v2, v13, v2, s20
	v_lshrrev_b32_e32 v2, 16, v2
	v_bfe_u32 v4, v15, 16, 1
	v_add3_u32 v4, v15, v4, s20
	v_and_or_b32 v10, v4, s21, v2
	v_bfe_u32 v2, v17, 16, 1
	v_add3_u32 v2, v17, v2, s20
	v_bfe_u32 v4, v19, 16, 1
	v_lshrrev_b32_e32 v2, 16, v2
	v_add3_u32 v4, v19, v4, s20
	v_and_or_b32 v11, v4, s21, v2
	v_or_b32_e32 v2, s12, v49
	v_and_b32_e32 v70, 0xff, v2
	v_and_b32_e32 v2, 0xffffff00, v2
	v_mul_u32_u24_e32 v2, 0x5600, v2
	v_lshl_add_u32 v2, v70, 7, v2
	v_and_or_b32 v8, v18, s21, v14
	ds_read2_b32 v[12:13], v52 offset0:16 offset1:24
	v_lshl_add_u64 v[4:5], v[44:45], 0, v[2:3]
	global_store_dwordx4 v[4:5], v[8:11], off
	ds_read2_b32 v[8:9], v52 offset0:49 offset1:57
	ds_read2_b32 v[10:11], v52 offset0:82 offset1:90
	ds_read2_b32 v[14:15], v52 offset0:115 offset1:123
	s_waitcnt lgkmcnt(3)
	v_bfe_u32 v2, v12, 16, 1
	v_add3_u32 v2, v12, v2, s20
	s_waitcnt lgkmcnt(2)
	v_bfe_u32 v4, v8, 16, 1
	ds_read2_b32 v[16:17], v52 offset0:148 offset1:156
	v_lshrrev_b32_e32 v2, 16, v2
	v_add3_u32 v4, v8, v4, s20
	ds_read2_b32 v[18:19], v52 offset0:181 offset1:189
	v_and_or_b32 v4, v4, s21, v2
	s_waitcnt lgkmcnt(3)
	v_bfe_u32 v2, v10, 16, 1
	v_add3_u32 v2, v10, v2, s20
	s_waitcnt lgkmcnt(2)
	v_bfe_u32 v5, v14, 16, 1
	ds_read2_b32 v[20:21], v52 offset0:214 offset1:222
	v_lshrrev_b32_e32 v2, 16, v2
	v_add3_u32 v5, v14, v5, s20
	ds_read2_b32 v[22:23], v52 offset0:247 offset1:255
	v_and_or_b32 v5, v5, s21, v2
	s_waitcnt lgkmcnt(3)
	v_bfe_u32 v2, v16, 16, 1
	v_add3_u32 v2, v16, v2, s20
	s_waitcnt lgkmcnt(2)
	v_bfe_u32 v6, v18, 16, 1
	v_lshrrev_b32_e32 v2, 16, v2
	v_add3_u32 v6, v18, v6, s20
	v_and_or_b32 v6, v6, s21, v2
	s_waitcnt lgkmcnt(1)
	v_bfe_u32 v2, v20, 16, 1
	v_add3_u32 v2, v20, v2, s20
	s_waitcnt lgkmcnt(0)
	v_bfe_u32 v7, v22, 16, 1
	v_lshrrev_b32_e32 v2, 16, v2
	v_add3_u32 v7, v22, v7, s20
	v_and_or_b32 v7, v7, s21, v2
	v_or_b32_e32 v2, s12, v50
	v_and_b32_e32 v70, 0xff, v2
	v_and_b32_e32 v2, 0xffffff00, v2
	v_mul_u32_u24_e32 v2, 0x5600, v2
	v_lshl_add_u32 v2, v70, 7, v2
	v_lshl_add_u64 v[24:25], v[44:45], 0, v[2:3]
	v_bfe_u32 v2, v13, 16, 1
	global_store_dwordx4 v[24:25], v[4:7], off
	v_add3_u32 v2, v13, v2, s20
	v_lshrrev_b32_e32 v2, 16, v2
	v_bfe_u32 v4, v9, 16, 1
	v_add3_u32 v4, v9, v4, s20
	v_and_or_b32 v4, v4, s21, v2
	v_bfe_u32 v2, v11, 16, 1
	v_add3_u32 v2, v11, v2, s20
	v_bfe_u32 v5, v15, 16, 1
	v_lshrrev_b32_e32 v2, 16, v2
	v_add3_u32 v5, v15, v5, s20
	v_and_or_b32 v5, v5, s21, v2
	v_bfe_u32 v2, v17, 16, 1
	v_add3_u32 v2, v17, v2, s20
	v_bfe_u32 v6, v19, 16, 1
	v_lshrrev_b32_e32 v2, 16, v2
	v_add3_u32 v6, v19, v6, s20
	v_and_or_b32 v6, v6, s21, v2
	v_bfe_u32 v2, v21, 16, 1
	v_add3_u32 v2, v21, v2, s20
	v_bfe_u32 v7, v23, 16, 1
	v_lshrrev_b32_e32 v2, 16, v2
	v_add3_u32 v7, v23, v7, s20
	v_and_or_b32 v7, v7, s21, v2
	v_or_b32_e32 v2, s12, v51
	v_and_b32_e32 v70, 0xff, v2
	v_and_b32_e32 v2, 0xffffff00, v2
	v_mul_u32_u24_e32 v2, 0x5600, v2
	v_lshl_add_u32 v2, v70, 7, v2
	v_lshl_add_u64 v[8:9], v[44:45], 0, v[2:3]
	global_store_dwordx4 v[8:9], v[4:7], off
	s_waitcnt lgkmcnt(0)
	s_mov_b64 s[12:13], 0

.LBB0_1161:
	s_mul_i32 s84, s1, 0x558000
	v_lshl_add_u32 v146, s1, 8, v1
	v_ashrrev_i32_e32 v147, 31, v146
	v_lshl_add_u64 v[144:145], v[146:147], 2, s[22:23]
	global_load_dword v166, v[144:145], off
	global_load_dword v150, v[144:145], off offset:576
	global_load_dword v148, v[144:145], off offset:640
	global_load_dword v142, v[144:145], off offset:704
	v_or_b32_e32 v164, 16, v146
	v_ashrrev_i32_e32 v165, 31, v164
	v_lshl_add_u64 v[152:153], v[164:165], 2, s[22:23]
	global_load_dword v162, v[152:153], off
	v_or_b32_e32 v160, 32, v146
	v_ashrrev_i32_e32 v161, 31, v160
	v_or_b32_e32 v156, 48, v146
	v_lshl_add_u64 v[152:153], v[160:161], 2, s[22:23]
	v_ashrrev_i32_e32 v157, 31, v156
	global_load_dword v158, v[152:153], off
	v_lshl_add_u64 v[152:153], v[156:157], 2, s[22:23]
	v_lshl_or_b32 v168, s0, 7, v149
	global_load_dword v154, v[152:153], off
	v_ashrrev_i32_e32 v169, 31, v168
	global_load_dword v152, v[144:145], off offset:512
	v_mov_b64_e32 v[144:145], s[16:17]
	s_movk_i32 s3, 0x80
	v_add_u32_e32 v159, 0x80, v146
	v_add_u32_e32 v157, 0x90, v146
	v_add_u32_e32 v155, 0xa0, v146
	v_add_u32_e32 v153, 0xb0, v146
	v_mad_i64_i32 v[170:171], s[0:1], v146, s3, v[144:145]
	v_lshrrev_b32_e32 v146, 6, v168
	v_lshlrev_b32_e32 v146, 15, v146
	v_and_b32_e32 v147, 63, v168
	v_lshl_add_u32 v146, v147, 1, v146
	v_add_u32_e32 v146, s84, v146
	v_mov_b32_e32 v147, 0
	v_lshl_add_u64 v[168:169], v[170:171], 0, v[146:147]
	v_readlane_b32 s62, v254, 51
	s_mov_b64 s[14:15], -1
	s_andn2_b64 vcc, exec, s[40:41]
	v_readlane_b32 s63, v254, 52
	s_movk_i32 s61, 0x110
	s_mov_b64 s[52:53], 0x5b000080
	s_waitcnt vmcnt(0)
	v_pk_mul_f32 v[128:129], v[128:129], v[166:167] op_sel_hi:[1,0]
	v_pk_mul_f32 v[120:121], v[120:121], v[166:167] op_sel_hi:[1,0]
	v_pk_mul_f32 v[170:171], v[118:119], v[166:167] op_sel_hi:[1,0]
	v_pk_mul_f32 v[118:119], v[116:117], v[166:167] op_sel_hi:[1,0]
	v_mul_f32_e32 v117, 0xbfb8aa3b, v128
	v_mul_f32_e32 v116, v128, v120
	v_exp_f32_e32 v117, v117
	v_mul_f32_e32 v120, 0xbfb8aa3b, v129
	v_exp_f32_e32 v120, v120
	v_pk_mul_f32 v[130:131], v[130:131], v[166:167] op_sel_hi:[1,0]
	v_add_f32_e32 v117, 1.0, v117
	v_rcp_f32_e32 v117, v117
	v_add_f32_e32 v120, 1.0, v120
	v_rcp_f32_e32 v120, v120
	v_pk_mul_f32 v[122:123], v[122:123], v[166:167] op_sel_hi:[1,0]
	v_mul_f32_e32 v116, v116, v117
	v_mul_f32_e32 v117, v129, v121
	v_mul_f32_e32 v117, v117, v120
	v_mul_f32_e32 v120, 0xbfb8aa3b, v130
	v_exp_f32_e32 v120, v120
	v_mul_f32_e32 v121, 0xbfb8aa3b, v131
	v_exp_f32_e32 v121, v121
	v_cvt_pk_bf16_f32 v116, v116, v117
	v_add_f32_e32 v120, 1.0, v120
	v_rcp_f32_e32 v120, v120
	v_add_f32_e32 v121, 1.0, v121
	v_rcp_f32_e32 v121, v121
	v_mul_f32_e32 v117, v130, v122
	v_mul_f32_e32 v117, v117, v120
	v_mul_f32_e32 v120, v131, v123
	v_pk_mul_f32 v[124:125], v[124:125], v[166:167] op_sel_hi:[1,0]
	v_mul_f32_e32 v120, v120, v121
	v_cvt_pk_bf16_f32 v117, v117, v120
	v_mul_f32_e32 v120, 0xbfb8aa3b, v124
	v_exp_f32_e32 v120, v120
	v_mul_f32_e32 v118, v124, v118
	v_pk_mul_f32 v[126:127], v[126:127], v[166:167] op_sel_hi:[1,0]
	v_mul_f32_e32 v119, v125, v119
	v_add_f32_e32 v120, 1.0, v120
	v_rcp_f32_e32 v120, v120
	v_mul_f32_e32 v121, 0xbfb8aa3b, v127
	v_exp_f32_e32 v121, v121
	v_pk_mul_f32 v[112:113], v[112:113], v[162:163] op_sel_hi:[1,0]
	v_mul_f32_e32 v118, v118, v120
	v_mul_f32_e32 v120, 0xbfb8aa3b, v125
	v_exp_f32_e32 v120, v120
	v_add_f32_e32 v121, 1.0, v121
	v_rcp_f32_e32 v121, v121
	v_pk_mul_f32 v[104:105], v[104:105], v[162:163] op_sel_hi:[1,0]
	v_add_f32_e32 v120, 1.0, v120
	v_rcp_f32_e32 v120, v120
	v_pk_mul_f32 v[114:115], v[114:115], v[162:163] op_sel_hi:[1,0]
	v_pk_mul_f32 v[106:107], v[106:107], v[162:163] op_sel_hi:[1,0]
	v_pk_mul_f32 v[108:109], v[108:109], v[162:163] op_sel_hi:[1,0]
	v_mul_f32_e32 v119, v119, v120
	v_mul_f32_e32 v120, 0xbfb8aa3b, v126
	v_exp_f32_e32 v120, v120
	v_cvt_pk_bf16_f32 v118, v118, v119
	v_mul_f32_e32 v119, v126, v170
	v_pk_mul_f32 v[110:111], v[110:111], v[162:163] op_sel_hi:[1,0]
	v_add_f32_e32 v120, 1.0, v120
	v_rcp_f32_e32 v120, v120
	v_pk_mul_f32 v[96:97], v[96:97], v[158:159] op_sel_hi:[1,0]
	v_pk_mul_f32 v[88:89], v[88:89], v[158:159] op_sel_hi:[1,0]
	v_pk_mul_f32 v[98:99], v[98:99], v[158:159] op_sel_hi:[1,0]
	v_mul_f32_e32 v119, v119, v120
	v_mul_f32_e32 v120, v127, v171
	v_mul_f32_e32 v120, v120, v121
	v_cvt_pk_bf16_f32 v119, v119, v120
	global_store_dwordx4 v[168:169], v[116:119], off
	v_pk_mul_f32 v[90:91], v[90:91], v[158:159] op_sel_hi:[1,0]
	v_pk_mul_f32 v[92:93], v[92:93], v[158:159] op_sel_hi:[1,0]
	v_pk_mul_f32 v[118:119], v[102:103], v[162:163] op_sel_hi:[1,0]
	v_pk_mul_f32 v[102:103], v[100:101], v[162:163] op_sel_hi:[1,0]
	v_mul_f32_e32 v101, 0xbfb8aa3b, v112
	v_mul_f32_e32 v100, v112, v104
	v_exp_f32_e32 v101, v101
	v_mul_f32_e32 v104, 0xbfb8aa3b, v113
	v_exp_f32_e32 v104, v104
	v_mul_f32_e32 v102, v108, v102
	v_add_f32_e32 v101, 1.0, v101
	v_rcp_f32_e32 v101, v101
	v_add_f32_e32 v104, 1.0, v104
	v_rcp_f32_e32 v104, v104
	v_mul_f32_e32 v103, v109, v103
	v_mul_f32_e32 v100, v100, v101
	v_mul_f32_e32 v101, v113, v105
	v_mul_f32_e32 v101, v101, v104
	v_mul_f32_e32 v104, 0xbfb8aa3b, v114
	v_exp_f32_e32 v104, v104
	v_mul_f32_e32 v105, 0xbfb8aa3b, v115
	v_exp_f32_e32 v105, v105
	v_cvt_pk_bf16_f32 v100, v100, v101
	v_add_f32_e32 v104, 1.0, v104
	v_rcp_f32_e32 v104, v104
	v_add_f32_e32 v105, 1.0, v105
	v_rcp_f32_e32 v105, v105
	v_mul_f32_e32 v101, v114, v106
	v_mul_f32_e32 v101, v101, v104
	v_mul_f32_e32 v104, v115, v107
	v_mul_f32_e32 v104, v104, v105
	v_cvt_pk_bf16_f32 v101, v101, v104
	v_mul_f32_e32 v104, 0xbfb8aa3b, v108
	v_exp_f32_e32 v104, v104
	v_mul_f32_e32 v105, 0xbfb8aa3b, v111
	v_exp_f32_e32 v105, v105
	v_mad_i64_i32 v[116:117], s[0:1], v164, s3, v[144:145]
	v_add_f32_e32 v104, 1.0, v104
	v_rcp_f32_e32 v104, v104
	v_add_f32_e32 v105, 1.0, v105
	v_rcp_f32_e32 v105, v105
	v_lshl_add_u64 v[116:117], v[116:117], 0, v[146:147]
	v_mul_f32_e32 v102, v102, v104
	v_mul_f32_e32 v104, 0xbfb8aa3b, v109
	v_exp_f32_e32 v104, v104
	v_pk_mul_f32 v[94:95], v[94:95], v[158:159] op_sel_hi:[1,0]
	v_pk_mul_f32 v[80:81], v[80:81], v[154:155] op_sel_hi:[1,0]
	v_pk_mul_f32 v[72:73], v[72:73], v[154:155] op_sel_hi:[1,0]
	v_add_f32_e32 v104, 1.0, v104
	v_rcp_f32_e32 v104, v104
	v_pk_mul_f32 v[82:83], v[82:83], v[154:155] op_sel_hi:[1,0]
	v_pk_mul_f32 v[74:75], v[74:75], v[154:155] op_sel_hi:[1,0]
	v_pk_mul_f32 v[76:77], v[76:77], v[154:155] op_sel_hi:[1,0]
	v_mul_f32_e32 v103, v103, v104
	v_mul_f32_e32 v104, 0xbfb8aa3b, v110
	v_exp_f32_e32 v104, v104
	v_cvt_pk_bf16_f32 v102, v102, v103
	v_mul_f32_e32 v103, v110, v118
	v_pk_mul_f32 v[78:79], v[78:79], v[154:155] op_sel_hi:[1,0]
	v_add_f32_e32 v104, 1.0, v104
	v_rcp_f32_e32 v104, v104
	v_pk_mul_f32 v[64:65], v[64:65], v[152:153] op_sel_hi:[1,0]
	v_pk_mul_f32 v[56:57], v[56:57], v[152:153] op_sel_hi:[1,0]
	v_pk_mul_f32 v[66:67], v[66:67], v[152:153] op_sel_hi:[1,0]
	v_mul_f32_e32 v103, v103, v104
	v_mul_f32_e32 v104, v111, v119
	v_mul_f32_e32 v104, v104, v105
	v_cvt_pk_bf16_f32 v103, v103, v104
	global_store_dwordx4 v[116:117], v[100:103], off
	v_pk_mul_f32 v[58:59], v[58:59], v[152:153] op_sel_hi:[1,0]
	v_pk_mul_f32 v[60:61], v[60:61], v[152:153] op_sel_hi:[1,0]
	v_pk_mul_f32 v[102:103], v[86:87], v[158:159] op_sel_hi:[1,0]
	v_pk_mul_f32 v[86:87], v[84:85], v[158:159] op_sel_hi:[1,0]
	v_mul_f32_e32 v85, 0xbfb8aa3b, v96
	v_mul_f32_e32 v84, v96, v88
	v_exp_f32_e32 v85, v85
	v_mul_f32_e32 v88, 0xbfb8aa3b, v97
	v_exp_f32_e32 v88, v88
	v_mul_f32_e32 v86, v92, v86
	v_add_f32_e32 v85, 1.0, v85
	v_rcp_f32_e32 v85, v85
	v_add_f32_e32 v88, 1.0, v88
	v_rcp_f32_e32 v88, v88
	v_mul_f32_e32 v87, v93, v87
	v_mul_f32_e32 v84, v84, v85
	v_mul_f32_e32 v85, v97, v89
	v_mul_f32_e32 v85, v85, v88
	v_mul_f32_e32 v88, 0xbfb8aa3b, v98
	v_exp_f32_e32 v88, v88
	v_mul_f32_e32 v89, 0xbfb8aa3b, v99
	v_exp_f32_e32 v89, v89
	v_cvt_pk_bf16_f32 v84, v84, v85
	v_add_f32_e32 v88, 1.0, v88
	v_rcp_f32_e32 v88, v88
	v_add_f32_e32 v89, 1.0, v89
	v_rcp_f32_e32 v89, v89
	v_mul_f32_e32 v85, v98, v90
	v_mul_f32_e32 v85, v85, v88
	v_mul_f32_e32 v88, v99, v91
	v_mul_f32_e32 v88, v88, v89
	v_cvt_pk_bf16_f32 v85, v85, v88
	v_mul_f32_e32 v88, 0xbfb8aa3b, v92
	v_exp_f32_e32 v88, v88
	v_mul_f32_e32 v89, 0xbfb8aa3b, v95
	v_exp_f32_e32 v89, v89
	v_mad_i64_i32 v[100:101], s[0:1], v160, s3, v[144:145]
	v_add_f32_e32 v88, 1.0, v88
	v_rcp_f32_e32 v88, v88
	v_add_f32_e32 v89, 1.0, v89
	v_rcp_f32_e32 v89, v89
	v_lshl_add_u64 v[100:101], v[100:101], 0, v[146:147]
	v_mul_f32_e32 v86, v86, v88
	v_mul_f32_e32 v88, 0xbfb8aa3b, v93
	v_exp_f32_e32 v88, v88
	v_pk_mul_f32 v[62:63], v[62:63], v[152:153] op_sel_hi:[1,0]
	v_pk_mul_f32 v[48:49], v[48:49], v[150:151] op_sel_hi:[1,0]
	v_pk_mul_f32 v[40:41], v[40:41], v[150:151] op_sel_hi:[1,0]
	v_add_f32_e32 v88, 1.0, v88
	v_rcp_f32_e32 v88, v88
	v_pk_mul_f32 v[50:51], v[50:51], v[150:151] op_sel_hi:[1,0]
	v_pk_mul_f32 v[42:43], v[42:43], v[150:151] op_sel_hi:[1,0]
	v_pk_mul_f32 v[44:45], v[44:45], v[150:151] op_sel_hi:[1,0]
	v_mul_f32_e32 v87, v87, v88
	v_mul_f32_e32 v88, 0xbfb8aa3b, v94
	v_exp_f32_e32 v88, v88
	v_cvt_pk_bf16_f32 v86, v86, v87
	v_mul_f32_e32 v87, v94, v102
	v_pk_mul_f32 v[46:47], v[46:47], v[150:151] op_sel_hi:[1,0]
	v_add_f32_e32 v88, 1.0, v88
	v_rcp_f32_e32 v88, v88
	v_pk_mul_f32 v[32:33], v[32:33], v[148:149] op_sel_hi:[1,0]
	v_pk_mul_f32 v[24:25], v[24:25], v[148:149] op_sel_hi:[1,0]
	v_pk_mul_f32 v[34:35], v[34:35], v[148:149] op_sel_hi:[1,0]
	v_mul_f32_e32 v87, v87, v88
	v_mul_f32_e32 v88, v95, v103
	v_mul_f32_e32 v88, v88, v89
	v_cvt_pk_bf16_f32 v87, v87, v88
	global_store_dwordx4 v[100:101], v[84:87], off
	v_pk_mul_f32 v[26:27], v[26:27], v[148:149] op_sel_hi:[1,0]
	v_pk_mul_f32 v[28:29], v[28:29], v[148:149] op_sel_hi:[1,0]
	v_pk_mul_f32 v[86:87], v[70:71], v[154:155] op_sel_hi:[1,0]
	v_pk_mul_f32 v[70:71], v[68:69], v[154:155] op_sel_hi:[1,0]
	v_mul_f32_e32 v69, 0xbfb8aa3b, v80
	v_mul_f32_e32 v68, v80, v72
	v_exp_f32_e32 v69, v69
	v_mul_f32_e32 v72, 0xbfb8aa3b, v81
	v_exp_f32_e32 v72, v72
	v_mul_f32_e32 v70, v76, v70
	v_add_f32_e32 v69, 1.0, v69
	v_rcp_f32_e32 v69, v69
	v_add_f32_e32 v72, 1.0, v72
	v_rcp_f32_e32 v72, v72
	v_mul_f32_e32 v71, v77, v71
	v_mul_f32_e32 v68, v68, v69
	v_mul_f32_e32 v69, v81, v73
	v_mul_f32_e32 v69, v69, v72
	v_mul_f32_e32 v72, 0xbfb8aa3b, v82
	v_exp_f32_e32 v72, v72
	v_mul_f32_e32 v73, 0xbfb8aa3b, v83
	v_exp_f32_e32 v73, v73
	v_cvt_pk_bf16_f32 v68, v68, v69
	v_add_f32_e32 v72, 1.0, v72
	v_rcp_f32_e32 v72, v72
	v_add_f32_e32 v73, 1.0, v73
	v_rcp_f32_e32 v73, v73
	v_mul_f32_e32 v69, v82, v74
	v_mul_f32_e32 v69, v69, v72
	v_mul_f32_e32 v72, v83, v75
	v_mul_f32_e32 v72, v72, v73
	v_cvt_pk_bf16_f32 v69, v69, v72
	v_mul_f32_e32 v72, 0xbfb8aa3b, v76
	v_exp_f32_e32 v72, v72
	v_mul_f32_e32 v73, 0xbfb8aa3b, v79
	v_exp_f32_e32 v73, v73
	v_mad_i64_i32 v[84:85], s[0:1], v156, s3, v[144:145]
	v_add_f32_e32 v72, 1.0, v72
	v_rcp_f32_e32 v72, v72
	v_add_f32_e32 v73, 1.0, v73
	v_rcp_f32_e32 v73, v73
	v_lshl_add_u64 v[84:85], v[84:85], 0, v[146:147]
	v_mul_f32_e32 v70, v70, v72
	v_mul_f32_e32 v72, 0xbfb8aa3b, v77
	v_exp_f32_e32 v72, v72
	v_pk_mul_f32 v[30:31], v[30:31], v[148:149] op_sel_hi:[1,0]
	v_pk_mul_f32 v[16:17], v[16:17], v[142:143] op_sel_hi:[1,0]
	v_pk_mul_f32 v[8:9], v[8:9], v[142:143] op_sel_hi:[1,0]
	v_add_f32_e32 v72, 1.0, v72
	v_rcp_f32_e32 v72, v72
	v_pk_mul_f32 v[18:19], v[18:19], v[142:143] op_sel_hi:[1,0]
	v_pk_mul_f32 v[10:11], v[10:11], v[142:143] op_sel_hi:[1,0]
	v_pk_mul_f32 v[12:13], v[12:13], v[142:143] op_sel_hi:[1,0]
	v_mul_f32_e32 v71, v71, v72
	v_mul_f32_e32 v72, 0xbfb8aa3b, v78
	v_exp_f32_e32 v72, v72
	v_cvt_pk_bf16_f32 v70, v70, v71
	v_mul_f32_e32 v71, v78, v86
	v_pk_mul_f32 v[14:15], v[14:15], v[142:143] op_sel_hi:[1,0]
	v_add_f32_e32 v72, 1.0, v72
	v_rcp_f32_e32 v72, v72
	s_nop 0
	v_mul_f32_e32 v71, v71, v72
	v_mul_f32_e32 v72, v79, v87
	v_mul_f32_e32 v72, v72, v73
	v_cvt_pk_bf16_f32 v71, v71, v72
	global_store_dwordx4 v[84:85], v[68:71], off
	s_nop 1
	v_pk_mul_f32 v[70:71], v[54:55], v[152:153] op_sel_hi:[1,0]
	v_pk_mul_f32 v[54:55], v[52:53], v[152:153] op_sel_hi:[1,0]
	v_mul_f32_e32 v53, 0xbfb8aa3b, v64
	v_mul_f32_e32 v52, v64, v56
	v_exp_f32_e32 v53, v53
	v_mul_f32_e32 v56, 0xbfb8aa3b, v65
	v_exp_f32_e32 v56, v56
	v_mul_f32_e32 v54, v60, v54
	v_add_f32_e32 v53, 1.0, v53
	v_rcp_f32_e32 v53, v53
	v_add_f32_e32 v56, 1.0, v56
	v_rcp_f32_e32 v56, v56
	v_mul_f32_e32 v55, v61, v55
	v_mul_f32_e32 v52, v52, v53
	v_mul_f32_e32 v53, v65, v57
	v_mul_f32_e32 v53, v53, v56
	v_mul_f32_e32 v56, 0xbfb8aa3b, v66
	v_exp_f32_e32 v56, v56
	v_mul_f32_e32 v57, 0xbfb8aa3b, v67
	v_exp_f32_e32 v57, v57
	v_cvt_pk_bf16_f32 v52, v52, v53
	v_add_f32_e32 v56, 1.0, v56
	v_rcp_f32_e32 v56, v56
	v_add_f32_e32 v57, 1.0, v57
	v_rcp_f32_e32 v57, v57
	v_mul_f32_e32 v53, v66, v58
	v_mul_f32_e32 v53, v53, v56
	v_mul_f32_e32 v56, v67, v59
	v_mul_f32_e32 v56, v56, v57
	v_cvt_pk_bf16_f32 v53, v53, v56
	v_mul_f32_e32 v56, 0xbfb8aa3b, v60
	v_exp_f32_e32 v56, v56
	v_mul_f32_e32 v57, 0xbfb8aa3b, v63
	v_exp_f32_e32 v57, v57
	v_mad_i64_i32 v[68:69], s[0:1], v159, s3, v[144:145]
	v_add_f32_e32 v56, 1.0, v56
	v_rcp_f32_e32 v56, v56
	v_add_f32_e32 v57, 1.0, v57
	v_rcp_f32_e32 v57, v57
	v_lshl_add_u64 v[68:69], v[68:69], 0, v[146:147]
	v_mul_f32_e32 v54, v54, v56
	v_mul_f32_e32 v56, 0xbfb8aa3b, v61
	v_exp_f32_e32 v56, v56
	s_nop 0
	v_add_f32_e32 v56, 1.0, v56
	v_rcp_f32_e32 v56, v56
	s_nop 0
	v_mul_f32_e32 v55, v55, v56
	v_mul_f32_e32 v56, 0xbfb8aa3b, v62
	v_exp_f32_e32 v56, v56
	v_cvt_pk_bf16_f32 v54, v54, v55
	v_mul_f32_e32 v55, v62, v70
	v_add_f32_e32 v56, 1.0, v56
	v_rcp_f32_e32 v56, v56
	s_nop 0
	v_mul_f32_e32 v55, v55, v56
	v_mul_f32_e32 v56, v63, v71
	v_mul_f32_e32 v56, v56, v57
	v_cvt_pk_bf16_f32 v55, v55, v56
	global_store_dwordx4 v[68:69], v[52:55], off
	s_nop 1
	v_pk_mul_f32 v[54:55], v[38:39], v[150:151] op_sel_hi:[1,0]
	v_pk_mul_f32 v[38:39], v[36:37], v[150:151] op_sel_hi:[1,0]
	v_mul_f32_e32 v37, 0xbfb8aa3b, v48
	v_mul_f32_e32 v36, v48, v40
	v_exp_f32_e32 v37, v37
	v_mul_f32_e32 v40, 0xbfb8aa3b, v49
	v_exp_f32_e32 v40, v40
	v_mul_f32_e32 v38, v44, v38
	v_add_f32_e32 v37, 1.0, v37
	v_rcp_f32_e32 v37, v37
	v_add_f32_e32 v40, 1.0, v40
	v_rcp_f32_e32 v40, v40
	v_mul_f32_e32 v39, v45, v39
	v_mul_f32_e32 v36, v36, v37
	v_mul_f32_e32 v37, v49, v41
	v_mul_f32_e32 v37, v37, v40
	v_mul_f32_e32 v40, 0xbfb8aa3b, v50
	v_exp_f32_e32 v40, v40
	v_mul_f32_e32 v41, 0xbfb8aa3b, v51
	v_exp_f32_e32 v41, v41
	v_cvt_pk_bf16_f32 v36, v36, v37
	v_add_f32_e32 v40, 1.0, v40
	v_rcp_f32_e32 v40, v40
	v_add_f32_e32 v41, 1.0, v41
	v_rcp_f32_e32 v41, v41
	v_mul_f32_e32 v37, v50, v42
	v_mul_f32_e32 v37, v37, v40
	v_mul_f32_e32 v40, v51, v43
	v_mul_f32_e32 v40, v40, v41
	v_cvt_pk_bf16_f32 v37, v37, v40
	v_mul_f32_e32 v40, 0xbfb8aa3b, v44
	v_exp_f32_e32 v40, v40
	v_mul_f32_e32 v41, 0xbfb8aa3b, v47
	v_exp_f32_e32 v41, v41
	v_mad_i64_i32 v[52:53], s[0:1], v157, s3, v[144:145]
	v_add_f32_e32 v40, 1.0, v40
	v_rcp_f32_e32 v40, v40
	v_add_f32_e32 v41, 1.0, v41
	v_rcp_f32_e32 v41, v41
	v_lshl_add_u64 v[52:53], v[52:53], 0, v[146:147]
	v_mul_f32_e32 v38, v38, v40
	v_mul_f32_e32 v40, 0xbfb8aa3b, v45
	v_exp_f32_e32 v40, v40
	s_nop 0
	v_add_f32_e32 v40, 1.0, v40
	v_rcp_f32_e32 v40, v40
	s_nop 0
	v_mul_f32_e32 v39, v39, v40
	v_mul_f32_e32 v40, 0xbfb8aa3b, v46
	v_exp_f32_e32 v40, v40
	v_cvt_pk_bf16_f32 v38, v38, v39
	v_mul_f32_e32 v39, v46, v54
	v_add_f32_e32 v40, 1.0, v40
	v_rcp_f32_e32 v40, v40
	s_nop 0
	v_mul_f32_e32 v39, v39, v40
	v_mul_f32_e32 v40, v47, v55
	v_mul_f32_e32 v40, v40, v41
	v_cvt_pk_bf16_f32 v39, v39, v40
	global_store_dwordx4 v[52:53], v[36:39], off
	s_nop 1
	v_pk_mul_f32 v[38:39], v[22:23], v[148:149] op_sel_hi:[1,0]
	v_pk_mul_f32 v[22:23], v[20:21], v[148:149] op_sel_hi:[1,0]
	v_mul_f32_e32 v21, 0xbfb8aa3b, v32
	v_mul_f32_e32 v20, v32, v24
	v_exp_f32_e32 v21, v21
	v_mul_f32_e32 v24, 0xbfb8aa3b, v33
	v_exp_f32_e32 v24, v24
	v_mul_f32_e32 v22, v28, v22
	v_add_f32_e32 v21, 1.0, v21
	v_rcp_f32_e32 v21, v21
	v_add_f32_e32 v24, 1.0, v24
	v_rcp_f32_e32 v24, v24
	v_mul_f32_e32 v23, v29, v23
	v_mul_f32_e32 v20, v20, v21
	v_mul_f32_e32 v21, v33, v25
	v_mul_f32_e32 v21, v21, v24
	v_mul_f32_e32 v24, 0xbfb8aa3b, v34
	v_exp_f32_e32 v24, v24
	v_mul_f32_e32 v25, 0xbfb8aa3b, v35
	v_exp_f32_e32 v25, v25
	v_cvt_pk_bf16_f32 v20, v20, v21
	v_add_f32_e32 v24, 1.0, v24
	v_rcp_f32_e32 v24, v24
	v_add_f32_e32 v25, 1.0, v25
	v_rcp_f32_e32 v25, v25
	v_mul_f32_e32 v21, v34, v26
	v_mul_f32_e32 v21, v21, v24
	v_mul_f32_e32 v24, v35, v27
	v_mul_f32_e32 v24, v24, v25
	v_cvt_pk_bf16_f32 v21, v21, v24
	v_mul_f32_e32 v24, 0xbfb8aa3b, v28
	v_exp_f32_e32 v24, v24
	v_mul_f32_e32 v25, 0xbfb8aa3b, v31
	v_exp_f32_e32 v25, v25
	v_mad_i64_i32 v[36:37], s[0:1], v155, s3, v[144:145]
	v_add_f32_e32 v24, 1.0, v24
	v_rcp_f32_e32 v24, v24
	v_add_f32_e32 v25, 1.0, v25
	v_rcp_f32_e32 v25, v25
	v_lshl_add_u64 v[36:37], v[36:37], 0, v[146:147]
	v_mul_f32_e32 v22, v22, v24
	v_mul_f32_e32 v24, 0xbfb8aa3b, v29
	v_exp_f32_e32 v24, v24
	s_nop 0
	v_add_f32_e32 v24, 1.0, v24
	v_rcp_f32_e32 v24, v24
	s_nop 0
	v_mul_f32_e32 v23, v23, v24
	v_mul_f32_e32 v24, 0xbfb8aa3b, v30
	v_exp_f32_e32 v24, v24
	v_cvt_pk_bf16_f32 v22, v22, v23
	v_mul_f32_e32 v23, v30, v38
	v_add_f32_e32 v24, 1.0, v24
	v_rcp_f32_e32 v24, v24
	s_nop 0
	v_mul_f32_e32 v23, v23, v24
	v_mul_f32_e32 v24, v31, v39
	v_mul_f32_e32 v24, v24, v25
	v_cvt_pk_bf16_f32 v23, v23, v24
	global_store_dwordx4 v[36:37], v[20:23], off
	s_nop 1
	v_pk_mul_f32 v[22:23], v[6:7], v[142:143] op_sel_hi:[1,0]
	v_pk_mul_f32 v[6:7], v[4:5], v[142:143] op_sel_hi:[1,0]
	v_mul_f32_e32 v5, 0xbfb8aa3b, v16
	v_mul_f32_e32 v4, v16, v8
	v_exp_f32_e32 v5, v5
	v_mul_f32_e32 v8, 0xbfb8aa3b, v17
	v_exp_f32_e32 v8, v8
	v_mul_f32_e32 v6, v12, v6
	v_add_f32_e32 v5, 1.0, v5
	v_rcp_f32_e32 v5, v5
	v_add_f32_e32 v8, 1.0, v8
	v_rcp_f32_e32 v8, v8
	v_mul_f32_e32 v7, v13, v7
	v_mul_f32_e32 v4, v4, v5
	v_mul_f32_e32 v5, v17, v9
	v_mul_f32_e32 v5, v5, v8
	v_mul_f32_e32 v8, 0xbfb8aa3b, v18
	v_exp_f32_e32 v8, v8
	v_mul_f32_e32 v9, 0xbfb8aa3b, v19
	v_exp_f32_e32 v9, v9
	v_cvt_pk_bf16_f32 v4, v4, v5
	v_add_f32_e32 v8, 1.0, v8
	v_rcp_f32_e32 v8, v8
	v_add_f32_e32 v9, 1.0, v9
	v_rcp_f32_e32 v9, v9
	v_mul_f32_e32 v5, v18, v10
	v_mul_f32_e32 v5, v5, v8
	v_mul_f32_e32 v8, v19, v11
	v_mul_f32_e32 v8, v8, v9
	v_cvt_pk_bf16_f32 v5, v5, v8
	v_mul_f32_e32 v8, 0xbfb8aa3b, v12
	v_exp_f32_e32 v8, v8
	v_mul_f32_e32 v9, 0xbfb8aa3b, v15
	v_exp_f32_e32 v9, v9
	v_mad_i64_i32 v[20:21], s[0:1], v153, s3, v[144:145]
	v_add_f32_e32 v8, 1.0, v8
	v_rcp_f32_e32 v8, v8
	v_add_f32_e32 v9, 1.0, v9
	v_rcp_f32_e32 v9, v9
	v_lshl_add_u64 v[20:21], v[20:21], 0, v[146:147]
	v_mul_f32_e32 v6, v6, v8
	v_mul_f32_e32 v8, 0xbfb8aa3b, v13
	v_exp_f32_e32 v8, v8
	s_nop 0
	v_add_f32_e32 v8, 1.0, v8
	v_rcp_f32_e32 v8, v8
	s_nop 0
	v_mul_f32_e32 v7, v7, v8
	v_mul_f32_e32 v8, 0xbfb8aa3b, v14
	v_exp_f32_e32 v8, v8
	v_cvt_pk_bf16_f32 v6, v6, v7
	v_mul_f32_e32 v7, v14, v22
	v_add_f32_e32 v8, 1.0, v8
	v_rcp_f32_e32 v8, v8
	s_nop 0
	v_mul_f32_e32 v7, v7, v8
	v_mul_f32_e32 v8, v15, v23
	v_mul_f32_e32 v8, v8, v9
	v_cvt_pk_bf16_f32 v7, v7, v8
	global_store_dwordx4 v[20:21], v[4:7], off
	s_cbranch_vccnz .LBB0_1154
	s_andn2_b64 vcc, exec, s[12:13]
	s_cbranch_vccnz .LBB0_1153
	s_barrier
	s_branch .LBB0_1153

.LBB0_1220:
	s_mov_b64 s[96:97], 0x8000
	v_mov_b32_e32 v1, v0
	s_mov_b64 s[6:7], s[72:73]
	s_waitcnt vmcnt(1)
	v_mov_b32_e32 v12, v0
	s_and_b64 vcc, exec, s[38:39]
	v_readfirstlane_b32 s18, v12
	s_cbranch_vccnz .LBB0_1294
	v_lshlrev_b32_e32 v1, 4, v12
	v_add_u32_e32 v2, 0x2000, v1
	v_ashrrev_i32_e32 v4, 31, v2
	v_lshrrev_b32_e32 v4, 22, v4
	v_add_u32_e32 v4, v2, v4
	v_ashrrev_i32_e32 v13, 10, v4
	v_mul_i32_i24_e32 v4, 0x400, v13
	v_sub_u32_e32 v2, v2, v4
	v_lshrrev_b32_e32 v4, 4, v2
	v_bitop3_b32 v2, v4, v2, 32 bitop3:0x6c
	v_ashrrev_i32_e32 v4, 31, v2
	v_lshrrev_b32_e32 v4, 26, v4
	v_add_u32_e32 v4, v2, v4
	s_waitcnt vmcnt(0)
	v_ashrrev_i32_e32 v14, 6, v4
	v_lshlrev_b32_e32 v6, 5, v13
	v_and_b32_e32 v4, 0xc0, v4
	v_and_b32_e32 v15, 32, v6
	v_sub_u32_e32 v2, v2, v4
	v_mov_b32_e32 v6, 1
	v_ashrrev_i16_sdwa v2, v6, sext(v2) dst_sel:DWORD dst_unused:UNUSED_PAD src0_sel:DWORD src1_sel:BYTE_0
	v_bfe_i32 v16, v2, 0, 16
	v_bfe_i32 v2, v12, 27, 1
	v_lshrrev_b32_e32 v2, 22, v2
	v_add_u32_e32 v2, v1, v2
	v_and_b32_e32 v2, 0xfffffc00, v2
	s_load_dwordx4 s[48:51], s[6:7], 0x90
	s_load_dwordx2 s[16:17], s[6:7], 0x8
	v_sub_u32_e32 v1, v1, v2
	v_lshrrev_b32_e32 v2, 4, v1
	v_ashrrev_i32_e32 v4, 31, v12
	v_bitop3_b32 v1, v2, v1, 32 bitop3:0x6c
	v_lshrrev_b32_e32 v4, 26, v4
	s_waitcnt lgkmcnt(0)
	v_lshlrev_b32_e32 v5, 3, v13
	v_ashrrev_i32_e32 v2, 31, v1
	v_add_u32_e32 v4, v12, v4
	s_add_u32 s0, s50, 0x28000000
	v_and_b32_e32 v5, 0xfffff0, v5
	v_lshrrev_b32_e32 v2, 26, v2
	v_ashrrev_i32_e32 v18, 6, v4
	s_addc_u32 s1, s51, 0
	v_add_u32_e32 v5, v14, v5
	s_movk_i32 s6, 0x40
	v_add_u32_e32 v2, v1, v2
	v_lshlrev_b32_e32 v4, 3, v18
	s_add_u32 s3, s50, 0x12a00000
	v_mul_lo_u32 v5, v5, s6
	v_ashrrev_i32_e32 v17, 6, v2
	v_and_b32_e32 v4, 0xfffff0, v4
	s_addc_u32 s26, s51, 0
	s_ashr_i32 s24, s18, 6
	v_or_b32_e32 v5, v5, v15
	v_add_u32_e32 v4, v17, v4
	v_and_b32_e32 v2, 0xc0, v2
	v_readlane_b32 s7, v253, 17
	s_ashr_i32 s19, s18, 8
	s_cbranch_scc0 .Lsp_p8
	s_setprio 1
.Lsp_p8:
	s_lshl_b32 s27, s24, 10
	v_add_lshl_u32 v186, v5, v16, 1
	v_mul_lo_u32 v4, v4, s6
	v_lshlrev_b32_e32 v5, 5, v18
	v_sub_u32_e32 v1, v1, v2
	s_mul_i32 s6, s7, 0x560000
	v_and_b32_e32 v19, 32, v5
	v_ashrrev_i16_sdwa v1, v6, sext(v1) dst_sel:DWORD dst_unused:UNUSED_PAD src0_sel:DWORD src1_sel:BYTE_0
	s_add_u32 s14, s3, s6
	s_mul_hi_i32 s6, s7, 0x560000
	v_or_b32_e32 v4, v4, v19
	v_bfe_i32 v20, v1, 0, 16
	s_addc_u32 s15, s26, s6
	s_add_i32 s28, s27, 0
	v_add_lshl_u32 v2, v4, v20, 1
	s_add_i32 m0, s28, 0x10000
	v_mov_b32_e32 v187, v3
	global_load_lds_dwordx4 v2, s[14:15]
	s_add_i32 m0, s28, 0x12000
	s_add_u32 s6, s14, 0x4000
	global_load_lds_dwordx4 v186, s[14:15]
	s_addc_u32 s7, s15, 0
	s_add_i32 m0, s28, 0x14000
	v_lshl_add_u64 v[10:11], s[14:15], 0, v[2:3]
	global_load_lds_dwordx4 v2, s[6:7]
	s_add_i32 m0, s28, 0x16000
	v_lshl_add_u64 v[8:9], s[14:15], 0, v[186:187]
	global_load_lds_dwordx4 v186, s[6:7]
	v_readlane_b32 s7, v253, 9
	s_mul_i32 s6, s7, 0x560000
	s_add_u32 s52, s0, s6
	s_mul_hi_i32 s6, s7, 0x560000
	s_addc_u32 s53, s1, s6
	s_add_i32 s29, s28, 0x2000
	s_mov_b32 m0, s28
	s_add_u32 s6, s52, 0x4000
	global_load_lds_dwordx4 v2, s[52:53]
	s_mov_b32 m0, s29
	s_addc_u32 s7, s53, 0
	s_add_i32 s30, s28, 0x4000
	global_load_lds_dwordx4 v186, s[52:53]
	s_mov_b32 m0, s30
	s_add_i32 s31, s28, 0x6000
	global_load_lds_dwordx4 v2, s[6:7]
	s_mov_b32 m0, s31
	s_cmp_eq_u32 s19, 1
	global_load_lds_dwordx4 v186, s[6:7]
	v_lshl_add_u64 v[4:5], s[52:53], 0, v[2:3]
	s_cselect_b64 s[6:7], -1, 0
	s_cmp_lg_u32 s19, 1
	v_lshl_add_u64 v[6:7], s[52:53], 0, v[186:187]
	s_cbranch_scc1 .LBB0_1223
	s_barrier
.LBB0_1223:
	s_add_u32 s12, s50, 0x18000000
	s_addc_u32 s13, s51, 0
	s_add_u32 s16, s16, 0x4000
	s_addc_u32 s17, s17, 0
	s_add_u32 s22, s50, 0x5b000000
	s_addc_u32 s23, s51, 0
	s_and_b32 s34, s24, 3
	s_add_i32 m0, s28, 0x18000
	v_lshl_add_u64 v[10:11], v[10:11], 0, s[96:97]
	s_lshl_b32 s37, s19, 13
	s_lshl_b32 s38, s34, 12
	s_waitcnt vmcnt(2)
	s_barrier
	global_load_lds_dwordx4 v[10:11], off
	v_lshl_add_u64 v[8:9], v[8:9], 0, s[96:97]
	s_add_i32 m0, s28, 0x1a000
	s_add_i32 s35, s28, 0x8000
	s_add_i32 s36, s28, 0xa000
	global_load_lds_dwordx4 v[8:9], off
	v_lshl_add_u64 v[4:5], v[4:5], 0, s[96:97]
	s_mov_b32 m0, s35
	s_add_u32 s24, s14, 0xc000
	global_load_lds_dwordx4 v[4:5], off
	v_lshl_add_u64 v[4:5], v[6:7], 0, s[96:97]
	s_mov_b32 m0, s36
	s_addc_u32 s25, s15, 0
	global_load_lds_dwordx4 v[4:5], off
	s_add_i32 m0, s28, 0x1c000
	v_lshl_add_u64 v[4:5], s[24:25], 0, v[2:3]
	global_load_lds_dwordx4 v[4:5], off
	v_lshl_add_u64 v[4:5], s[24:25], 0, v[186:187]
	s_add_i32 m0, s28, 0x1e000
	s_movk_i32 s24, 0x40
	global_load_lds_dwordx4 v[4:5], off
	v_bfe_u32 v4, v12, 4, 2
	v_and_b32_e32 v5, 15, v12
	v_lshlrev_b32_e32 v6, 4, v4
	v_lshl_or_b32 v1, s19, 6, v5
	v_lshl_or_b32 v5, v5, 6, v6
	v_lshlrev_b32_e32 v6, 2, v12
	v_and_b32_e32 v6, 32, v6
	v_bitop3_b32 v7, v5, s37, v6 bitop3:0xde
	v_bitop3_b32 v197, v5, s38, v6 bitop3:0xde
	v_lshlrev_b32_e32 v5, 2, v4
	v_lshl_or_b32 v240, s34, 5, v5
	v_cmp_eq_u32_e64 s[38:39], 0, v4
	v_lshrrev_b32_e32 v5, 1, v18
	v_mul_lo_u32 v4, v17, s24
	s_mov_b32 s25, 0x400
	s_cmpk_lt_u32 s18, 0x100
	v_mad_u64_u32 v[4:5], s[18:19], v5, s25, v[4:5]
	v_or_b32_e32 v4, v4, v19
	v_add_lshl_u32 v4, v4, v20, 1
	v_mov_b32_e32 v5, v3
	s_mov_b64 s[40:41], 0xc000
	v_lshl_add_u64 v[188:189], v[4:5], 0, s[40:41]
	v_lshrrev_b32_e32 v5, 1, v13
	v_mul_lo_u32 v4, v14, s24
	v_mad_u64_u32 v[4:5], s[18:19], v5, s25, v[4:5]
	s_waitcnt vmcnt(6)
	v_or_b32_e32 v4, v4, v15
	v_add_lshl_u32 v4, v4, v16, 1
	v_mov_b32_e32 v5, v3
	s_cselect_b64 s[44:45], -1, 0
	s_mov_b32 s37, 0
	v_lshl_add_u64 v[190:191], v[4:5], 0, s[40:41]
	v_add_u32_e32 v241, 0, v7
	v_readlane_b32 s50, v253, 17
	v_readlane_b32 s51, v253, 9
	s_barrier
	s_branch .LBB0_1226

.LBB0_1236:
	s_add_u32 s56, s14, 0x10000
	v_mov_b32_e32 v4, 0
	s_addc_u32 s57, s15, 0
	s_mov_b32 s58, -2
	s_waitcnt lgkmcnt(0)
	v_mov_b32_e32 v5, v4
	v_mov_b32_e32 v6, v4
	v_mov_b32_e32 v7, v4
	v_mov_b32_e32 v8, v4
	v_mov_b32_e32 v9, v4
	v_mov_b32_e32 v10, v4
	v_mov_b32_e32 v11, v4
	v_mov_b32_e32 v20, v4
	v_mov_b32_e32 v21, v4
	v_mov_b32_e32 v22, v4
	v_mov_b32_e32 v23, v4
	v_mov_b32_e32 v24, v4
	v_mov_b32_e32 v25, v4
	v_mov_b32_e32 v26, v4
	v_mov_b32_e32 v27, v4
	v_mov_b32_e32 v36, v4
	v_mov_b32_e32 v37, v4
	v_mov_b32_e32 v38, v4
	v_mov_b32_e32 v39, v4
	v_mov_b32_e32 v40, v4
	v_mov_b32_e32 v41, v4
	v_mov_b32_e32 v42, v4
	v_mov_b32_e32 v43, v4
	v_mov_b32_e32 v52, v4
	v_mov_b32_e32 v53, v4
	v_mov_b32_e32 v54, v4
	v_mov_b32_e32 v55, v4
	v_mov_b32_e32 v56, v4
	v_mov_b32_e32 v57, v4
	v_mov_b32_e32 v58, v4
	v_mov_b32_e32 v59, v4
	v_mov_b32_e32 v12, v4
	v_mov_b32_e32 v13, v4
	v_mov_b32_e32 v14, v4
	v_mov_b32_e32 v15, v4
	v_mov_b32_e32 v16, v4
	v_mov_b32_e32 v17, v4
	v_mov_b32_e32 v18, v4
	v_mov_b32_e32 v19, v4
	v_mov_b32_e32 v28, v4
	v_mov_b32_e32 v29, v4
	v_mov_b32_e32 v30, v4
	v_mov_b32_e32 v31, v4
	v_mov_b32_e32 v32, v4
	v_mov_b32_e32 v33, v4
	v_mov_b32_e32 v34, v4
	v_mov_b32_e32 v35, v4
	v_mov_b32_e32 v44, v4
	v_mov_b32_e32 v45, v4
	v_mov_b32_e32 v46, v4
	v_mov_b32_e32 v47, v4
	v_mov_b32_e32 v48, v4
	v_mov_b32_e32 v49, v4
	v_mov_b32_e32 v50, v4
	v_mov_b32_e32 v51, v4
	v_mov_b32_e32 v64, v4
	v_mov_b32_e32 v65, v4
	v_mov_b32_e32 v66, v4
	v_mov_b32_e32 v67, v4
	v_mov_b32_e32 v72, v4
	v_mov_b32_e32 v73, v4
	v_mov_b32_e32 v74, v4
	v_mov_b32_e32 v75, v4
	v_mov_b32_e32 v84, v4
	v_mov_b32_e32 v85, v4
	v_mov_b32_e32 v86, v4
	v_mov_b32_e32 v87, v4
	v_mov_b32_e32 v88, v4
	v_mov_b32_e32 v89, v4
	v_mov_b32_e32 v90, v4
	v_mov_b32_e32 v91, v4
	v_mov_b32_e32 v100, v4
	v_mov_b32_e32 v101, v4
	v_mov_b32_e32 v102, v4
	v_mov_b32_e32 v103, v4
	v_mov_b32_e32 v104, v4
	v_mov_b32_e32 v105, v4
	v_mov_b32_e32 v106, v4
	v_mov_b32_e32 v107, v4
	v_mov_b32_e32 v116, v4
	v_mov_b32_e32 v117, v4
	v_mov_b32_e32 v118, v4
	v_mov_b32_e32 v119, v4
	v_mov_b32_e32 v120, v4
	v_mov_b32_e32 v121, v4
	v_mov_b32_e32 v122, v4
	v_mov_b32_e32 v123, v4
	v_mov_b32_e32 v132, v4
	v_mov_b32_e32 v133, v4
	v_mov_b32_e32 v134, v4
	v_mov_b32_e32 v135, v4
	v_mov_b32_e32 v136, v4
	v_mov_b32_e32 v137, v4
	v_mov_b32_e32 v138, v4
	v_mov_b32_e32 v139, v4
	v_mov_b32_e32 v92, v4
	v_mov_b32_e32 v93, v4
	v_mov_b32_e32 v94, v4
	v_mov_b32_e32 v95, v4
	v_mov_b32_e32 v96, v4
	v_mov_b32_e32 v97, v4
	v_mov_b32_e32 v98, v4
	v_mov_b32_e32 v99, v4
	v_mov_b32_e32 v108, v4
	v_mov_b32_e32 v109, v4
	v_mov_b32_e32 v110, v4
	v_mov_b32_e32 v111, v4
	v_mov_b32_e32 v112, v4
	v_mov_b32_e32 v113, v4
	v_mov_b32_e32 v114, v4
	v_mov_b32_e32 v115, v4
	v_mov_b32_e32 v124, v4
	v_mov_b32_e32 v125, v4
	v_mov_b32_e32 v126, v4
	v_mov_b32_e32 v127, v4
	v_mov_b32_e32 v128, v4
	v_mov_b32_e32 v129, v4
	v_mov_b32_e32 v130, v4
	v_mov_b32_e32 v131, v4
	v_mov_b32_e32 v140, v4
	v_mov_b32_e32 v141, v4
	v_mov_b32_e32 v142, v4
	v_mov_b32_e32 v143, v4
	v_mov_b32_e32 v144, v4
	v_mov_b32_e32 v145, v4
	v_mov_b32_e32 v146, v4
	v_mov_b32_e32 v147, v4
.LBB0_1237:
	s_add_u32 s14, s52, 0x10000
	s_addc_u32 s15, s53, 0
	s_add_i32 s59, 0, 0x10000
	s_cmpk_eq_i32 s58, 0xa8
	s_cselect_b32 s25, s43, s15
	s_cselect_b32 s24, s42, s14
	s_cselect_b32 s19, s47, s57
	s_cselect_b32 s18, s46, s56
	s_add_i32 s60, 0, 0x14000
	v_add_u32_e32 v80, s59, v197
	v_add_u32_e32 v160, s60, v197
	ds_read_b128 v[60:63], v80
	ds_read_b128 v[68:71], v80 offset:1024
	ds_read_b128 v[76:79], v80 offset:2048
	ds_read_b128 v[80:83], v80 offset:3072
	ds_read_b128 v[148:151], v160
	ds_read_b128 v[152:155], v160 offset:1024
	ds_read_b128 v[156:159], v160 offset:2048
	ds_read_b128 v[160:163], v160 offset:3072
	v_lshl_add_u64 v[184:185], s[52:53], 0, v[188:189]
	s_add_i32 m0, s28, 0xc000
	ds_read_b128 v[164:167], v241
	ds_read_b128 v[168:171], v241 offset:1024
	ds_read_b128 v[172:175], v241 offset:2048
	ds_read_b128 v[176:179], v241 offset:3072
	ds_read_b128 v[180:183], v241 offset:4096
	ds_read_b128 v[206:209], v241 offset:5120
	ds_read_b128 v[210:213], v241 offset:6144
	ds_read_b128 v[224:227], v241 offset:7168
	global_load_lds_dwordx4 v[184:185], off
	v_lshl_add_u64 v[184:185], s[52:53], 0, v[190:191]
	s_add_i32 m0, s28, 0xe000
	s_nop 0
	global_load_lds_dwordx4 v[184:185], off
	s_waitcnt vmcnt(8)
	s_waitcnt lgkmcnt(0)
	s_barrier
	s_waitcnt lgkmcnt(0)
	v_mfma_f32_16x16x32_bf16 v[144:147], v[60:63], v[164:167], v[144:147]
	v_mfma_f32_16x16x32_bf16 v[140:143], v[76:79], v[164:167], v[140:143]
	v_mfma_f32_16x16x32_bf16 v[128:131], v[60:63], v[172:175], v[128:131]
	v_mfma_f32_16x16x32_bf16 v[124:127], v[76:79], v[172:175], v[124:127]
	v_mfma_f32_16x16x32_bf16 v[112:115], v[60:63], v[180:183], v[112:115]
	v_mfma_f32_16x16x32_bf16 v[108:111], v[76:79], v[180:183], v[108:111]
	v_mfma_f32_16x16x32_bf16 v[96:99], v[60:63], v[210:213], v[96:99]
	v_mfma_f32_16x16x32_bf16 v[92:95], v[76:79], v[210:213], v[92:95]
	v_mfma_f32_16x16x32_bf16 v[144:147], v[68:71], v[168:171], v[144:147]
	v_mfma_f32_16x16x32_bf16 v[140:143], v[80:83], v[168:171], v[140:143]
	v_mfma_f32_16x16x32_bf16 v[128:131], v[68:71], v[176:179], v[128:131]
	v_mfma_f32_16x16x32_bf16 v[124:127], v[80:83], v[176:179], v[124:127]
	v_mfma_f32_16x16x32_bf16 v[112:115], v[68:71], v[206:209], v[112:115]
	v_mfma_f32_16x16x32_bf16 v[108:111], v[80:83], v[206:209], v[108:111]
	v_mfma_f32_16x16x32_bf16 v[96:99], v[68:71], v[224:227], v[96:99]
	v_mfma_f32_16x16x32_bf16 v[92:95], v[80:83], v[224:227], v[92:95]
	v_mfma_f32_16x16x32_bf16 v[136:139], v[148:151], v[164:167], v[136:139]
	v_mfma_f32_16x16x32_bf16 v[132:135], v[156:159], v[164:167], v[132:135]
	v_mfma_f32_16x16x32_bf16 v[120:123], v[148:151], v[172:175], v[120:123]
	v_mfma_f32_16x16x32_bf16 v[116:119], v[156:159], v[172:175], v[116:119]
	v_mfma_f32_16x16x32_bf16 v[104:107], v[148:151], v[180:183], v[104:107]
	v_mfma_f32_16x16x32_bf16 v[100:103], v[156:159], v[180:183], v[100:103]
	v_mfma_f32_16x16x32_bf16 v[88:91], v[148:151], v[210:213], v[88:91]
	v_mfma_f32_16x16x32_bf16 v[84:87], v[156:159], v[210:213], v[84:87]
	v_mfma_f32_16x16x32_bf16 v[136:139], v[152:155], v[168:171], v[136:139]
	v_mfma_f32_16x16x32_bf16 v[132:135], v[160:163], v[168:171], v[132:135]
	v_mfma_f32_16x16x32_bf16 v[120:123], v[152:155], v[176:179], v[120:123]
	v_mfma_f32_16x16x32_bf16 v[116:119], v[160:163], v[176:179], v[116:119]
	v_mfma_f32_16x16x32_bf16 v[104:107], v[152:155], v[206:209], v[104:107]
	v_mfma_f32_16x16x32_bf16 v[100:103], v[160:163], v[206:209], v[100:103]
	v_mfma_f32_16x16x32_bf16 v[88:91], v[152:155], v[224:227], v[88:91]
	v_mfma_f32_16x16x32_bf16 v[84:87], v[160:163], v[224:227], v[84:87]
	s_barrier
	s_add_i32 s52, s59, s27
	v_lshl_add_u64 v[184:185], s[18:19], 0, v[2:3]
	s_mov_b32 m0, s52
	ds_read_b128 v[164:167], v241 offset:16384
	ds_read_b128 v[168:171], v241 offset:17408
	ds_read_b128 v[172:175], v241 offset:18432
	ds_read_b128 v[176:179], v241 offset:19456
	ds_read_b128 v[180:183], v241 offset:20480
	ds_read_b128 v[206:209], v241 offset:21504
	ds_read_b128 v[210:213], v241 offset:22528
	ds_read_b128 v[224:227], v241 offset:23552
	global_load_lds_dwordx4 v[184:185], off
	s_add_i32 m0, s52, 0x2000
	s_add_u32 s52, s18, 0x4000
	v_lshl_add_u64 v[192:193], s[18:19], 0, v[186:187]
	s_addc_u32 s53, s19, 0
	s_add_i32 s59, s60, s27
	global_load_lds_dwordx4 v[192:193], off
	v_lshl_add_u64 v[214:215], s[52:53], 0, v[2:3]
	s_mov_b32 m0, s59
	v_lshl_add_u64 v[228:229], s[24:25], 0, v[186:187]
	global_load_lds_dwordx4 v[214:215], off
	v_lshl_add_u64 v[214:215], s[52:53], 0, v[186:187]
	s_add_i32 m0, s59, 0x2000
	s_nop 0
	global_load_lds_dwordx4 v[214:215], off
	v_lshl_add_u64 v[214:215], s[24:25], 0, v[2:3]
	s_mov_b32 m0, s28
	s_nop 0
	global_load_lds_dwordx4 v[214:215], off
	s_mov_b32 m0, s29
	s_nop 0
	global_load_lds_dwordx4 v[228:229], off
	s_waitcnt vmcnt(8)
	s_waitcnt lgkmcnt(0)
	s_barrier
	s_waitcnt lgkmcnt(0)
	v_mfma_f32_16x16x32_bf16 v[72:75], v[60:63], v[164:167], v[72:75]
	v_mfma_f32_16x16x32_bf16 v[64:67], v[76:79], v[164:167], v[64:67]
	v_mfma_f32_16x16x32_bf16 v[48:51], v[60:63], v[172:175], v[48:51]
	v_mfma_f32_16x16x32_bf16 v[44:47], v[76:79], v[172:175], v[44:47]
	v_mfma_f32_16x16x32_bf16 v[32:35], v[60:63], v[180:183], v[32:35]
	v_mfma_f32_16x16x32_bf16 v[28:31], v[76:79], v[180:183], v[28:31]
	v_mfma_f32_16x16x32_bf16 v[16:19], v[60:63], v[210:213], v[16:19]
	v_mfma_f32_16x16x32_bf16 v[12:15], v[76:79], v[210:213], v[12:15]
	v_mfma_f32_16x16x32_bf16 v[72:75], v[68:71], v[168:171], v[72:75]
	v_mfma_f32_16x16x32_bf16 v[64:67], v[80:83], v[168:171], v[64:67]
	v_mfma_f32_16x16x32_bf16 v[48:51], v[68:71], v[176:179], v[48:51]
	v_mfma_f32_16x16x32_bf16 v[44:47], v[80:83], v[176:179], v[44:47]
	v_mfma_f32_16x16x32_bf16 v[32:35], v[68:71], v[206:209], v[32:35]
	v_mfma_f32_16x16x32_bf16 v[28:31], v[80:83], v[206:209], v[28:31]
	v_mfma_f32_16x16x32_bf16 v[16:19], v[68:71], v[224:227], v[16:19]
	v_mfma_f32_16x16x32_bf16 v[12:15], v[80:83], v[224:227], v[12:15]
	v_mfma_f32_16x16x32_bf16 v[56:59], v[148:151], v[164:167], v[56:59]
	v_mfma_f32_16x16x32_bf16 v[52:55], v[156:159], v[164:167], v[52:55]
	v_mfma_f32_16x16x32_bf16 v[40:43], v[148:151], v[172:175], v[40:43]
	v_mfma_f32_16x16x32_bf16 v[36:39], v[156:159], v[172:175], v[36:39]
	v_mfma_f32_16x16x32_bf16 v[24:27], v[148:151], v[180:183], v[24:27]
	v_mfma_f32_16x16x32_bf16 v[20:23], v[156:159], v[180:183], v[20:23]
	v_mfma_f32_16x16x32_bf16 v[8:11], v[148:151], v[210:213], v[8:11]
	v_mfma_f32_16x16x32_bf16 v[4:7], v[156:159], v[210:213], v[4:7]
	v_mfma_f32_16x16x32_bf16 v[56:59], v[152:155], v[168:171], v[56:59]
	v_mfma_f32_16x16x32_bf16 v[52:55], v[160:163], v[168:171], v[52:55]
	v_mfma_f32_16x16x32_bf16 v[40:43], v[152:155], v[176:179], v[40:43]
	v_mfma_f32_16x16x32_bf16 v[36:39], v[160:163], v[176:179], v[36:39]
	v_mfma_f32_16x16x32_bf16 v[24:27], v[152:155], v[206:209], v[24:27]
	v_mfma_f32_16x16x32_bf16 v[20:23], v[160:163], v[206:209], v[20:23]
	v_mfma_f32_16x16x32_bf16 v[8:11], v[152:155], v[224:227], v[8:11]
	v_mfma_f32_16x16x32_bf16 v[4:7], v[160:163], v[224:227], v[4:7]
	s_barrier
	s_add_i32 s52, 0, 0x18000
	s_add_i32 s53, 0, 0x1c000
	v_add_u32_e32 v80, s52, v197
	v_add_u32_e32 v160, s53, v197
	ds_read_b128 v[60:63], v80
	ds_read_b128 v[68:71], v80 offset:1024
	ds_read_b128 v[76:79], v80 offset:2048
	ds_read_b128 v[80:83], v80 offset:3072
	ds_read_b128 v[148:151], v160
	ds_read_b128 v[152:155], v160 offset:1024
	ds_read_b128 v[156:159], v160 offset:2048
	ds_read_b128 v[160:163], v160 offset:3072
	s_add_u32 s24, s24, 0x4000
	s_addc_u32 s25, s25, 0
	s_mov_b32 m0, s30
	v_lshl_add_u64 v[230:231], s[24:25], 0, v[2:3]
	ds_read_b128 v[164:167], v241 offset:32768
	ds_read_b128 v[168:171], v241 offset:33792
	ds_read_b128 v[172:175], v241 offset:34816
	ds_read_b128 v[176:179], v241 offset:35840
	ds_read_b128 v[180:183], v241 offset:36864
	ds_read_b128 v[206:209], v241 offset:37888
	ds_read_b128 v[210:213], v241 offset:38912
	ds_read_b128 v[224:227], v241 offset:39936
	global_load_lds_dwordx4 v[230:231], off
	v_lshl_add_u64 v[230:231], s[24:25], 0, v[186:187]
	s_mov_b32 m0, s31
	s_nop 0
	global_load_lds_dwordx4 v[230:231], off
	s_waitcnt vmcnt(8)
	s_waitcnt lgkmcnt(0)
	s_barrier
	s_waitcnt lgkmcnt(0)
	v_mfma_f32_16x16x32_bf16 v[144:147], v[60:63], v[164:167], v[144:147]
	v_mfma_f32_16x16x32_bf16 v[140:143], v[76:79], v[164:167], v[140:143]
	v_mfma_f32_16x16x32_bf16 v[128:131], v[60:63], v[172:175], v[128:131]
	v_mfma_f32_16x16x32_bf16 v[124:127], v[76:79], v[172:175], v[124:127]
	v_mfma_f32_16x16x32_bf16 v[112:115], v[60:63], v[180:183], v[112:115]
	v_mfma_f32_16x16x32_bf16 v[108:111], v[76:79], v[180:183], v[108:111]
	v_mfma_f32_16x16x32_bf16 v[96:99], v[60:63], v[210:213], v[96:99]
	v_mfma_f32_16x16x32_bf16 v[92:95], v[76:79], v[210:213], v[92:95]
	v_mfma_f32_16x16x32_bf16 v[144:147], v[68:71], v[168:171], v[144:147]
	v_mfma_f32_16x16x32_bf16 v[140:143], v[80:83], v[168:171], v[140:143]
	v_mfma_f32_16x16x32_bf16 v[128:131], v[68:71], v[176:179], v[128:131]
	v_mfma_f32_16x16x32_bf16 v[124:127], v[80:83], v[176:179], v[124:127]
	v_mfma_f32_16x16x32_bf16 v[112:115], v[68:71], v[206:209], v[112:115]
	v_mfma_f32_16x16x32_bf16 v[108:111], v[80:83], v[206:209], v[108:111]
	v_mfma_f32_16x16x32_bf16 v[96:99], v[68:71], v[224:227], v[96:99]
	v_mfma_f32_16x16x32_bf16 v[92:95], v[80:83], v[224:227], v[92:95]
	v_mfma_f32_16x16x32_bf16 v[136:139], v[148:151], v[164:167], v[136:139]
	v_mfma_f32_16x16x32_bf16 v[132:135], v[156:159], v[164:167], v[132:135]
	v_mfma_f32_16x16x32_bf16 v[120:123], v[148:151], v[172:175], v[120:123]
	v_mfma_f32_16x16x32_bf16 v[116:119], v[156:159], v[172:175], v[116:119]
	v_mfma_f32_16x16x32_bf16 v[104:107], v[148:151], v[180:183], v[104:107]
	v_mfma_f32_16x16x32_bf16 v[100:103], v[156:159], v[180:183], v[100:103]
	v_mfma_f32_16x16x32_bf16 v[88:91], v[148:151], v[210:213], v[88:91]
	v_mfma_f32_16x16x32_bf16 v[84:87], v[156:159], v[210:213], v[84:87]
	v_mfma_f32_16x16x32_bf16 v[136:139], v[152:155], v[168:171], v[136:139]
	v_mfma_f32_16x16x32_bf16 v[132:135], v[160:163], v[168:171], v[132:135]
	v_mfma_f32_16x16x32_bf16 v[120:123], v[152:155], v[176:179], v[120:123]
	v_mfma_f32_16x16x32_bf16 v[116:119], v[160:163], v[176:179], v[116:119]
	v_mfma_f32_16x16x32_bf16 v[104:107], v[152:155], v[206:209], v[104:107]
	v_mfma_f32_16x16x32_bf16 v[100:103], v[160:163], v[206:209], v[100:103]
	v_mfma_f32_16x16x32_bf16 v[88:91], v[152:155], v[224:227], v[88:91]
	v_mfma_f32_16x16x32_bf16 v[84:87], v[160:163], v[224:227], v[84:87]
	s_barrier
	s_add_i32 s24, s52, s27
	v_lshl_add_u64 v[184:185], v[184:185], 0, s[96:97]
	s_mov_b32 m0, s24
	ds_read_b128 v[164:167], v241 offset:49152
	ds_read_b128 v[168:171], v241 offset:50176
	ds_read_b128 v[172:175], v241 offset:51200
	ds_read_b128 v[176:179], v241 offset:52224
	ds_read_b128 v[180:183], v241 offset:53248
	ds_read_b128 v[206:209], v241 offset:54272
	ds_read_b128 v[210:213], v241 offset:55296
	ds_read_b128 v[224:227], v241 offset:56320
	global_load_lds_dwordx4 v[184:185], off
	s_add_i32 m0, s24, 0x2000
	s_add_u32 s18, s18, 0xc000
	v_lshl_add_u64 v[184:185], v[192:193], 0, s[96:97]
	s_addc_u32 s19, s19, 0
	s_add_i32 s24, s53, s27
	global_load_lds_dwordx4 v[184:185], off
	v_lshl_add_u64 v[184:185], s[18:19], 0, v[2:3]
	s_mov_b32 m0, s24
	s_nop 0
	global_load_lds_dwordx4 v[184:185], off
	v_lshl_add_u64 v[184:185], s[18:19], 0, v[186:187]
	s_add_i32 m0, s24, 0x2000
	s_nop 0
	global_load_lds_dwordx4 v[184:185], off
	v_lshl_add_u64 v[184:185], v[214:215], 0, s[96:97]
	s_mov_b32 m0, s35
	s_nop 0
	global_load_lds_dwordx4 v[184:185], off
	v_lshl_add_u64 v[184:185], v[228:229], 0, s[96:97]
	s_mov_b32 m0, s36
	s_nop 0
	global_load_lds_dwordx4 v[184:185], off
	s_waitcnt vmcnt(8)
	s_waitcnt lgkmcnt(0)
	s_barrier
	s_waitcnt lgkmcnt(0)
	v_mfma_f32_16x16x32_bf16 v[72:75], v[60:63], v[164:167], v[72:75]
	v_mfma_f32_16x16x32_bf16 v[64:67], v[76:79], v[164:167], v[64:67]
	v_mfma_f32_16x16x32_bf16 v[48:51], v[60:63], v[172:175], v[48:51]
	v_mfma_f32_16x16x32_bf16 v[44:47], v[76:79], v[172:175], v[44:47]
	v_mfma_f32_16x16x32_bf16 v[32:35], v[60:63], v[180:183], v[32:35]
	v_mfma_f32_16x16x32_bf16 v[28:31], v[76:79], v[180:183], v[28:31]
	v_mfma_f32_16x16x32_bf16 v[16:19], v[60:63], v[210:213], v[16:19]
	v_mfma_f32_16x16x32_bf16 v[12:15], v[76:79], v[210:213], v[12:15]
	v_mfma_f32_16x16x32_bf16 v[72:75], v[68:71], v[168:171], v[72:75]
	v_mfma_f32_16x16x32_bf16 v[64:67], v[80:83], v[168:171], v[64:67]
	v_mfma_f32_16x16x32_bf16 v[48:51], v[68:71], v[176:179], v[48:51]
	v_mfma_f32_16x16x32_bf16 v[44:47], v[80:83], v[176:179], v[44:47]
	v_mfma_f32_16x16x32_bf16 v[32:35], v[68:71], v[206:209], v[32:35]
	v_mfma_f32_16x16x32_bf16 v[28:31], v[80:83], v[206:209], v[28:31]
	v_mfma_f32_16x16x32_bf16 v[16:19], v[68:71], v[224:227], v[16:19]
	v_mfma_f32_16x16x32_bf16 v[12:15], v[80:83], v[224:227], v[12:15]
	v_mfma_f32_16x16x32_bf16 v[56:59], v[148:151], v[164:167], v[56:59]
	v_mfma_f32_16x16x32_bf16 v[52:55], v[156:159], v[164:167], v[52:55]
	v_mfma_f32_16x16x32_bf16 v[40:43], v[148:151], v[172:175], v[40:43]
	v_mfma_f32_16x16x32_bf16 v[36:39], v[156:159], v[172:175], v[36:39]
	v_mfma_f32_16x16x32_bf16 v[24:27], v[148:151], v[180:183], v[24:27]
	v_mfma_f32_16x16x32_bf16 v[20:23], v[156:159], v[180:183], v[20:23]
	v_mfma_f32_16x16x32_bf16 v[8:11], v[148:151], v[210:213], v[8:11]
	v_mfma_f32_16x16x32_bf16 v[4:7], v[156:159], v[210:213], v[4:7]
	v_mfma_f32_16x16x32_bf16 v[56:59], v[152:155], v[168:171], v[56:59]
	v_mfma_f32_16x16x32_bf16 v[52:55], v[160:163], v[168:171], v[52:55]
	v_mfma_f32_16x16x32_bf16 v[40:43], v[152:155], v[176:179], v[40:43]
	v_mfma_f32_16x16x32_bf16 v[36:39], v[160:163], v[176:179], v[36:39]
	v_mfma_f32_16x16x32_bf16 v[24:27], v[152:155], v[206:209], v[24:27]
	v_mfma_f32_16x16x32_bf16 v[20:23], v[160:163], v[206:209], v[20:23]
	v_mfma_f32_16x16x32_bf16 v[8:11], v[152:155], v[224:227], v[8:11]
	v_mfma_f32_16x16x32_bf16 v[4:7], v[160:163], v[224:227], v[4:7]
	s_barrier
	s_add_i32 s58, s58, 2
	s_add_u32 s56, s56, 0x10000
	s_addc_u32 s57, s57, 0
	s_cmpk_gt_u32 s58, 0xa9
	s_mov_b64 s[52:53], s[14:15]
	s_cbranch_scc0 .LBB0_1237
	s_and_b64 vcc, exec, s[44:45]
	s_cbranch_vccz .LBB0_1240
	s_barrier
